# P2b loop-top wait ladder leaves the previous unit's 12 blob stores in flight on the back edge (full drain only at loop entry); otherwise as previous best
# baseline (speedup 1.0000x reference)
; #define LAS __attribute__((address_space(3)))
; #define MFMA32(a, b, c) __builtin_amdgcn_mfma_f32_32x32x16_bf16((a), (b), (c), 0, 0, 0)
; __device__ __forceinline__ void gla_prep_phase(LAS unsigned char* lds, const GlaPrepArgs& A, int bid, int G) {
;     ...
;     int unit = bid;
;     if (unit < nunits) GLA_PREFETCH(unit);
;     ...
;     if (w < 4) {
;         const int rt = w >> 1, ct = w & 1, r = lane & 31, hh = lane >> 5;
;         f32x16 af = zero16(), ab = zero16();
;         if (rt >= ct) { const LAS unsigned char* ia = lds + L_QGF + (32 * rt + r) * QS_ + 16 * hh; const LAS unsigned char* ib = lds + L_KGF + (32 * ct + r) * QS_ + 16 * hh;
; #pragma unroll
;             for (int ks = 0; ks < 8; ++ks) af = MFMA32(*(const LAS bf16x8*)(ia + 32 * ks), *(const LAS bf16x8*)(ib + 32 * ks), af); }
;         if (rt <= ct) { const LAS unsigned char* ia = lds + L_QGB + (32 * rt + r) * QS_ + 16 * hh; const LAS unsigned char* ib = lds + L_KGB + (32 * ct + r) * QS_ + 16 * hh;
; #pragma unroll
;             for (int ks = 0; ks < 8; ++ks) ab = MFMA32(*(const LAS bf16x8*)(ia + 32 * ks), *(const LAS bf16x8*)(ib + 32 * ks), ab); }
;         const int j = 32 * ct + r;
; #pragma unroll
;         for (int reg = 0; reg < 16; ++reg) { const int i = 32 * rt + (reg & 3) + 8 * (reg >> 2) + 4 * hh;
;             const float val = (i >= j ? af[reg] : 0.f) + (i <= j ? ab[reg] : 0.f);
.LBB0_418:
	s_andn2_b64 vcc, exec, s[2:3]
	s_cbranch_vccnz .LBB0_489
	v_readlane_b32 s2, v251, 43
	v_writelane_b32 v254, s42, 55
	v_mov_b32_e32 v70, v0
	v_readlane_b32 s3, v251, 44
	v_writelane_b32 v254, s43, 56
	s_andn2_b64 vcc, exec, s[2:3]
	v_readfirstlane_b32 s3, v70
	s_cbranch_vccnz .LBB0_434
	v_ashrrev_i32_e32 v72, 3, v70
	v_readlane_b32 s4, v251, 45
	v_ashrrev_i32_e32 v73, 31, v72
	v_readlane_b32 s5, v251, 46
	v_readlane_b32 s76, v251, 25
	v_readlane_b32 s77, v251, 26
	s_waitcnt vmcnt(0)
	v_lshl_add_u64 v[4:5], s[4:5], 0, v[72:73]
	v_lshlrev_b64 v[4:5], 8, v[4:5]
	v_lshlrev_b32_e32 v3, 4, v70
	v_lshl_add_u64 v[4:5], s[76:77], 0, v[4:5]
	v_and_b32_e32 v130, 0x70, v3
	v_ashrrev_i32_e32 v74, 5, v70
	v_lshl_add_u64 v[4:5], v[4:5], 0, v[130:131]
	v_readlane_b32 s6, v251, 49
	v_ashrrev_i32_e32 v75, 31, v74
	global_load_dwordx4 v[34:37], v[4:5], off offset:128
	v_and_b32_e32 v4, 0x1f0, v3
	v_mov_b32_e32 v5, v131
	v_readlane_b32 s7, v251, 50
	v_lshl_add_u64 v[8:9], s[4:5], 0, v[74:75]
	v_add_u32_e32 v12, 0x200, v70
	v_lshl_add_u64 v[6:7], s[6:7], 0, v[4:5]
	v_lshlrev_b64 v[8:9], 11, v[8:9]
	v_ashrrev_i32_e32 v76, 5, v12
	v_lshl_add_u64 v[8:9], v[6:7], 0, v[8:9]
	v_ashrrev_i32_e32 v77, 31, v76
	global_load_dwordx4 v[38:41], v[8:9], off
	v_lshl_add_u64 v[8:9], s[4:5], 0, v[76:77]
	v_lshlrev_b64 v[8:9], 11, v[8:9]
	v_lshl_add_u64 v[8:9], v[6:7], 0, v[8:9]
	global_load_dwordx4 v[42:45], v[8:9], off
	v_add_u32_e32 v8, 0x400, v70
	v_ashrrev_i32_e32 v78, 5, v8
	v_ashrrev_i32_e32 v79, 31, v78
	v_lshl_add_u64 v[8:9], s[4:5], 0, v[78:79]
	v_lshlrev_b64 v[8:9], 11, v[8:9]
	v_lshl_add_u64 v[8:9], v[6:7], 0, v[8:9]
	global_load_dwordx4 v[46:49], v[8:9], off
	v_add_u32_e32 v8, 0x600, v70
	v_ashrrev_i32_e32 v80, 5, v8
	v_ashrrev_i32_e32 v81, 31, v80
	v_lshl_add_u64 v[8:9], s[4:5], 0, v[80:81]
	v_lshlrev_b64 v[8:9], 11, v[8:9]
	v_ashrrev_i32_e32 v82, 4, v70
	v_lshl_add_u64 v[6:7], v[6:7], 0, v[8:9]
	v_readlane_b32 s6, v251, 53
	v_ashrrev_i32_e32 v83, 31, v82
	global_load_dwordx4 v[50:53], v[6:7], off
	v_and_b32_e32 v6, 0xf0, v3
	v_mov_b32_e32 v7, v131
	v_readlane_b32 s7, v251, 54
	v_lshl_add_u64 v[10:11], s[4:5], 0, v[82:83]
	v_lshlrev_b64 v[10:11], 11, v[10:11]
	v_lshl_add_u64 v[8:9], s[6:7], 0, v[6:7]
	v_ashrrev_i32_e32 v84, 4, v12
	v_lshl_add_u64 v[10:11], v[8:9], 0, v[10:11]
	v_ashrrev_i32_e32 v85, 31, v84
	global_load_dwordx4 v[54:57], v[10:11], off
	global_load_dwordx4 v[58:61], v[10:11], off offset:1024
	v_lshl_add_u64 v[10:11], s[4:5], 0, v[84:85]
	v_lshlrev_b64 v[10:11], 11, v[10:11]
	v_lshl_add_u64 v[8:9], v[8:9], 0, v[10:11]
	global_load_dwordx4 v[62:65], v[8:9], off
	global_load_dwordx4 v[66:69], v[8:9], off offset:1024
	s_ashr_i32 s2, s3, 6
	s_cmp_gt_i32 s2, 3
	v_lshrrev_b32_e32 v12, 2, v70
	v_and_b32_e32 v86, 0x7f, v70
	v_readlane_b32 s4, v254, 2
	s_cselect_b64 s[70:71], -1, 0
	s_lshl_b32 s5, s2, 4
	v_and_b32_e32 v12, 8, v12
	v_lshl_add_u32 v98, v70, 2, s4
	v_lshl_add_u32 v99, v86, 2, s4
	s_movk_i32 s4, 0x80
	v_and_or_b32 v13, s5, 48, v12
	v_readlane_b32 s5, v254, 3
	v_cmp_gt_u32_e64 s[36:37], s4, v70
	s_add_i32 s4, s2, -4
	v_mov_b32_e32 v14, s5
	s_ashr_i32 s5, s3, 7
	s_and_b32 s6, s2, 1
	s_cmp_ge_i32 s5, s6
	s_cselect_b64 s[38:39], -1, 0
	s_lshl_b32 s7, s5, 5
	v_readlane_b32 s34, v254, 1
	v_writelane_b32 v254, s38, 53
	s_cmp_le_i32 s5, s6
	v_lshlrev_b32_e32 v20, 1, v70
	v_writelane_b32 v254, s39, 54
	s_cselect_b64 s[38:39], -1, 0
	s_andn2_b32 s3, s3, 63
	v_and_b32_e32 v20, 62, v20
	s_add_i32 s3, s34, s3
	v_add_u32_e32 v20, s3, v20
	s_ashr_i32 s3, s2, 31
	s_lshl_b64 s[74:75], s[2:3], 12
	s_movk_i32 s3, 0x210
	v_ashrrev_i32_e32 v10, 7, v70
	v_writelane_b32 v254, s38, 57
	v_mul_lo_u32 v22, v74, s3
	v_mul_lo_u32 v23, v76, s3
	v_mul_lo_u32 v24, v78, s3
	v_mul_lo_u32 v25, v80, s3
	s_movk_i32 s3, 0x1100
	v_lshl_add_u32 v87, v10, 11, 0
	v_and_b32_e32 v11, 0x3fffff80, v70
	v_writelane_b32 v254, s39, 58
	v_cmp_lt_i32_e64 s[38:39], 0, v10
	v_cmp_gt_i32_e64 s[40:41], 0, v10
	v_cmp_lt_i32_e64 s[42:43], 1, v10
	v_cmp_gt_i32_e64 s[44:45], 1, v10
	v_cmp_lt_i32_e64 s[46:47], 2, v10
	v_cmp_gt_i32_e64 s[48:49], 2, v10
	v_cmp_lt_i32_e64 s[50:51], 3, v10
	v_cmp_gt_i32_e64 s[52:53], 3, v10
	v_mul_lo_u32 v10, v10, s3
	s_lshl_b32 s3, s4, 2
	v_lshl_add_u32 v100, v11, 2, v99
	v_and_b32_e32 v11, 31, v70
	s_and_b32 s3, s3, 0xfffffe0
	v_or_b32_e32 v28, s3, v11
	s_lshl_b32 s3, s4, 5
	s_movk_i32 s54, 0x110
	s_and_b32 s3, s3, 0xe0
	v_mul_lo_u32 v28, v28, s54
	s_add_i32 s3, s3, 0
	v_add_u32_e32 v28, s3, v28
	s_lshl_b32 s3, s2, 2
	s_and_b32 s3, s3, 0xfffffe0
	v_or_b32_e32 v29, s3, v11
	s_lshl_b32 s3, s2, 5
	s_and_b32 s3, s3, 0xe0
	v_readlane_b32 s5, v254, 4
	v_lshrrev_b32_e32 v21, 1, v70
	v_mul_lo_u32 v29, v29, s54
	s_add_i32 s3, s3, 0
	v_lshl_or_b32 v16, s6, 5, v11
	v_mov_b32_e32 v18, s5
	v_readlane_b32 s5, v254, 5
	v_and_b32_e32 v21, 16, v21
	v_add_u32_e32 v29, s3, v29
	s_add_i32 s3, s2, 4
	v_lshl_add_u32 v19, v16, 1, s5
	v_add_u32_e32 v21, s5, v21
	s_lshl_b32 s5, s3, 2
	s_and_b32 s5, s5, 0xfffffe0
	v_or_b32_e32 v30, s5, v11
	s_lshl_b32 s5, s3, 5
	s_and_b32 s5, s5, 0xe0
	v_add_u32_e32 v8, s34, v4
	s_lshl_b32 s34, s4, 10
	v_mul_lo_u32 v30, v30, s54
	s_add_i32 s5, s5, 0
; #define LAS __attribute__((address_space(3)))
; #define MFMA32(a, b, c) __builtin_amdgcn_mfma_f32_32x32x16_bf16((a), (b), (c), 0, 0, 0)
; __device__ __forceinline__ unsigned pkbf(float a, float b) { bf16x2_t v = __builtin_convertvector((f32x2_t){a, b}, bf16x2_t); return __builtin_bit_cast(unsigned, v); }
; __device__ __forceinline__ void gla_prep_phase(LAS unsigned char* lds, const GlaPrepArgs& A, int bid, int G) {
;     ...
;     if (w < 4) {
;         const int rt = w >> 1, ct = w & 1, r = lane & 31, hh = lane >> 5;
;         f32x16 af = zero16(), ab = zero16();
;         if (rt >= ct) { const LAS unsigned char* ia = lds + L_QGF + (32 * rt + r) * QS_ + 16 * hh; const LAS unsigned char* ib = lds + L_KGF + (32 * ct + r) * QS_ + 16 * hh;
; #pragma unroll
;             for (int ks = 0; ks < 8; ++ks) af = MFMA32(*(const LAS bf16x8*)(ia + 32 * ks), *(const LAS bf16x8*)(ib + 32 * ks), af); }
;         if (rt <= ct) { const LAS unsigned char* ia = lds + L_QGB + (32 * rt + r) * QS_ + 16 * hh; const LAS unsigned char* ib = lds + L_KGB + (32 * ct + r) * QS_ + 16 * hh;
; #pragma unroll
;             for (int ks = 0; ks < 8; ++ks) ab = MFMA32(*(const LAS bf16x8*)(ia + 32 * ks), *(const LAS bf16x8*)(ib + 32 * ks), ab); }
;         const int j = 32 * ct + r;
; #pragma unroll
;         for (int reg = 0; reg < 16; ++reg) { const int i = 32 * rt + (reg & 3) + 8 * (reg >> 2) + 4 * hh;
;             const float val = (i >= j ? af[reg] : 0.f) + (i <= j ? ab[reg] : 0.f);
;             *(LAS unsigned short*)(lds + L_AS + i * AS_ + j * 2) = (unsigned short)(pkbf(val, 0.f) & 0xffffu); }
;     } else {
;         const int b0 = w - 4;
; #pragma unroll
;         for (int k = 0; k < 16; ++k) {
;             const int wh = k >> 2, b = b0 + 4 * (k & 3); v4u f; int off;
;             if (wh == 0)      { f = gdn::frag_rm_perm(lds + L_QGF, QS_, b >> 3, b & 7, lane); off = B_QGF; }
;             else if (wh == 1) { f = gdn::frag_rm_perm(lds + L_QGB, QS_, b >> 3, b & 7, lane); off = B_QGB; }
;             else if (wh == 2) { f = frag_tr_nat(lds + L_KDF, QS_, 32 * (b >> 2), b & 3, lane); off = B_KDTF; }
;             else              { f = frag_tr_nat(lds + L_KDB, QS_, 32 * (b >> 2), b & 3, lane); off = B_KDTB; }
;             *(v4u*)(blob + off + b * 1024 + lane * 16) = f;
;         }
	s_lshl_b32 s4, s4, 3
	s_lshl_b32 s72, s2, 12
	s_lshl_b32 s84, s2, 10
	v_add_u32_e32 v30, s5, v30
	s_add_i32 s5, s2, 8
	s_and_b32 s4, s4, 0x7fffffe0
	s_lshl_b32 s2, s2, 3
	v_or_b32_e32 v32, s4, v11
	s_and_b32 s2, s2, 0x7fffffe0
	v_lshlrev_b32_e32 v103, 1, v32
	v_or_b32_e32 v32, s2, v11
	s_lshl_b32 s2, s3, 3
	s_and_b32 s2, s2, 0x7fffffe0
	v_mad_u32_u24 v101, v13, s54, 0
	v_mad_u32_u24 v102, v13, s54, v14
	v_bfe_u32 v13, v70, 5, 1
	v_lshlrev_b32_e32 v104, 1, v32
	v_or_b32_e32 v32, s2, v11
	s_lshl_b32 s2, s5, 3
	v_lshlrev_b32_e32 v15, 4, v13
	s_and_b32 s2, s2, 0x7fffffe0
	v_lshl_or_b32 v13, v13, 2, s7
	s_lshl_b32 s85, s3, 10
	v_lshlrev_b32_e32 v105, 1, v32
	v_or_b32_e32 v32, s2, v11
	v_cmp_gt_i32_e64 s[2:3], v13, v16
	v_or_b32_e32 v33, 1, v13
	v_lshlrev_b32_e32 v106, 1, v32
	v_writelane_b32 v255, s2, 1
	s_lshl_b32 s6, s5, 2
	s_and_b32 s6, s6, 0xfffffe0
	v_writelane_b32 v255, s3, 2
	s_movk_i32 s2, 0x90
	v_mul_lo_u32 v32, v13, s2
	v_cmp_lt_i32_e64 s[2:3], v33, v16
	v_or_b32_e32 v33, 2, v13
	v_or_b32_e32 v31, s6, v11
	v_writelane_b32 v255, s2, 3
	s_lshl_b32 s6, s5, 5
	s_and_b32 s6, s6, 0xe0
	v_writelane_b32 v255, s3, 4
	v_cmp_lt_i32_e64 s[2:3], v33, v16
	v_mul_lo_u32 v31, v31, s54
	s_add_i32 s6, s6, 0
	v_writelane_b32 v255, s2, 5
	v_readlane_b32 s78, v251, 47
	v_or_b32_e32 v14, s7, v11
	v_writelane_b32 v255, s3, 6
	v_cmp_gt_i32_e64 s[2:3], v33, v16
	v_or_b32_e32 v33, 3, v13
	v_add_u32_e32 v31, s6, v31
	v_writelane_b32 v255, s2, 7
	s_lshl_b32 s86, s5, 10
	v_readlane_b32 s79, v251, 48
	v_writelane_b32 v255, s3, 8
	v_cmp_lt_i32_e64 s[2:3], v33, v16
	v_mul_lo_u32 v14, v14, s54
	v_mad_u32_u24 v17, v16, s54, 0
	v_writelane_b32 v255, s2, 9
	v_mad_u32_u24 v18, v16, s54, v18
	v_mul_lo_u32 v26, v82, s54
	v_writelane_b32 v255, s3, 10
	v_cmp_gt_i32_e64 s[2:3], v33, v16
	v_or_b32_e32 v33, 8, v13
	v_mul_lo_u32 v27, v84, s54
	v_writelane_b32 v255, s2, 11
	v_cmp_lt_i32_e64 s[54:55], v13, v16
	v_lshl_add_u64 v[90:91], s[78:79], 0, v[4:5]
	v_writelane_b32 v255, s3, 12
	v_cmp_lt_i32_e64 s[2:3], v33, v16
	v_readlane_b32 s78, v251, 51
	v_and_b32_e32 v2, 63, v70
	v_writelane_b32 v255, s2, 15
	v_lshl_add_u32 v3, v72, 7, 0
	v_add_u32_e32 v9, 0, v6
	v_writelane_b32 v255, s3, 16
	v_cmp_gt_i32_e64 s[2:3], v33, v16
	v_or_b32_e32 v33, 9, v13
	v_add_u32_e32 v14, 0, v14
	v_writelane_b32 v255, s2, 17
	v_lshl_or_b32 v10, v86, 1, v10
	v_mul_u32_u24_e32 v11, 0x90, v11
	v_writelane_b32 v255, s3, 18
	v_cmp_lt_i32_e64 s[2:3], v33, v16
	v_readlane_b32 s79, v251, 52
	v_readlane_b32 s67, v252, 54
	v_writelane_b32 v255, s2, 19
	v_mov_b32_e32 v71, v131
	v_lshlrev_b32_e32 v88, 4, v2
	v_writelane_b32 v255, s3, 20
	v_cmp_gt_i32_e64 s[2:3], v33, v16
	v_or_b32_e32 v33, 10, v13
	v_mov_b32_e32 v89, v131
	v_writelane_b32 v255, s2, 21
	s_ashr_i32 s73, s72, 31
	v_lshl_add_u64 v[92:93], s[78:79], 0, v[6:7]
	v_writelane_b32 v255, s3, 22
	v_cmp_lt_i32_e64 s[2:3], v33, v16
	v_lshl_add_u64 v[94:95], s[76:77], 0, v[130:131]
	s_lshl_b32 s67, s67, 6
	v_writelane_b32 v255, s2, 23
	s_lshl_b32 s87, s93, 6
	v_add_u32_e32 v107, v3, v130
	v_writelane_b32 v255, s3, 24
	v_cmp_gt_i32_e64 s[2:3], v33, v16
	v_or_b32_e32 v33, 11, v13
	v_add_u32_e32 v108, v8, v22
	v_writelane_b32 v255, s2, 25
	v_add_u32_e32 v109, v8, v23
	v_add_u32_e32 v110, v8, v24
	v_writelane_b32 v255, s3, 26
	v_cmp_lt_i32_e64 s[2:3], v33, v16
	v_add_u32_e32 v111, v8, v25
	v_add_u32_e32 v112, v9, v26
	v_writelane_b32 v255, s2, 27
	v_add_u32_e32 v113, v9, v27
	v_add_u32_e32 v114, 0, v10
	v_writelane_b32 v255, s3, 28
	v_cmp_gt_i32_e64 s[2:3], v33, v16
	v_or_b32_e32 v33, 16, v13
	v_add_u32_e32 v115, v28, v12
	v_writelane_b32 v255, s2, 29
	v_add_u32_e32 v116, v29, v12
	v_add_u32_e32 v117, v30, v12
	v_writelane_b32 v255, s3, 30
	v_cmp_lt_i32_e64 s[2:3], v33, v16
	v_add_u32_e32 v118, v31, v12
	v_add_u32_e32 v119, v17, v15
	v_writelane_b32 v255, s2, 31
	v_add_u32_e32 v120, v18, v15
	v_add_u32_e32 v121, v19, v32
	v_writelane_b32 v255, s3, 32
	v_cmp_gt_i32_e64 s[2:3], v33, v16
	v_or_b32_e32 v33, 17, v13
	v_add_u32_e32 v123, v21, v11
	v_writelane_b32 v255, s2, 33
	v_lshlrev_b32_e32 v130, 3, v2
	v_add_u32_e32 v124, v14, v15
	v_writelane_b32 v255, s3, 34
	v_cmp_lt_i32_e64 s[2:3], v33, v16
	v_readlane_b32 s76, v254, 16
	s_nop 0
	v_writelane_b32 v255, s2, 35
	s_nop 1
	v_writelane_b32 v255, s3, 36
	v_cmp_gt_i32_e64 s[2:3], v33, v16
	v_or_b32_e32 v33, 18, v13
	v_cmp_gt_i32_e64 s[94:95], v33, v16
	v_writelane_b32 v255, s2, 37
	s_nop 1
	v_writelane_b32 v255, s3, 38
	v_cmp_lt_i32_e64 s[2:3], v33, v16
	v_or_b32_e32 v33, 19, v13
	v_cmp_lt_i32_e64 s[68:69], v33, v16
	v_writelane_b32 v255, s2, 39
	s_nop 1
	v_writelane_b32 v255, s3, 40
	v_cmp_gt_i32_e64 s[2:3], v33, v16
	v_or_b32_e32 v33, 24, v13
	v_cmp_lt_i32_e64 s[4:5], v33, v16
	v_cmp_gt_i32_e64 s[6:7], v33, v16
	v_or_b32_e32 v33, 25, v13
	v_cmp_lt_i32_e64 s[60:61], v33, v16
	v_cmp_gt_i32_e64 s[62:63], v33, v16
	v_or_b32_e32 v33, 26, v13
	v_or_b32_e32 v13, 27, v13
	v_cmp_lt_i32_e64 s[56:57], v13, v16
	v_cmp_gt_i32_e64 s[58:59], v13, v16
	v_mul_u32_u24_e32 v13, 0x210, v12
	v_cmp_lt_i32_e64 s[64:65], v33, v16
	v_cmp_gt_i32_e64 s[82:83], v33, v16
	v_add_u32_e32 v122, v20, v13
	s_waitcnt vmcnt(0)
	s_nop 0
	s_branch .LBB0_423

; #define LAS __attribute__((address_space(3)))
; #define LBAR() do { asm volatile("s_waitcnt lgkmcnt(0)" ::: "memory"); __builtin_amdgcn_s_barrier(); asm volatile("" ::: "memory"); } while (0)
; __device__ __forceinline__ float logsig2(float x) { const float xc = fminf(fmaxf(x, -60.f), 60.f); return -__builtin_amdgcn_logf(1.0f + __builtin_amdgcn_exp2f(-1.4426950408889634f * xc)); }
; __device__ __forceinline__ void gla_prep_phase(LAS unsigned char* lds, const GlaPrepArgs& A, int bid, int G) {
;     ...
;     const int h = (unit / NCH) % 4;
;     unsigned char* blob = A.blobA + (size_t)unit * BLOBA; unsigned char* blobB = A.blobB + (size_t)unit * BLOBB;
;     *(LAS f32x4*)(lds + L_R + (tid >> 3) * 128 + (tid & 7) * 16) = pr;
; #pragma unroll
;     for (int i = 0; i < 4; ++i) { const int id = i * 512 + tid; *(LAS v4u*)(lds + L_V + (id >> 5) * VS_ + (id & 31) * 16) = pv[i]; }
; #pragma unroll
;     for (int i = 0; i < 2; ++i) { const int id = i * 512 + tid; *(LAS v4u*)(lds + L_QGF + (id >> 4) * QS_ + (id & 15) * 16) = pq[i]; *(LAS v4u*)(lds + L_KGF + (id >> 4) * QS_ + (id & 15) * 16) = pk[i]; }
;     LBAR();
;     {
;         const int dd = tid & 127, pg = tid >> 7, d = h * 128 + dd;
;         float wf[16], wb[16];
; #pragma unroll
;         for (int i = 0; i < 16; ++i) { wf[i] = A.w2f[i * 512 + d]; wb[i] = A.w2b[i * 512 + d]; }
;         const float bf_ = A.b2f[d], bb_ = A.b2b[d];
;         float lf[16], lb[16];
; #pragma unroll
;         for (int pp = 0; pp < 16; ++pp) {
;             const LAS float* rr = (const LAS float*)(lds + L_R) + (pg * 16 + pp) * 32;
;             float xf = bf_, xb = bb_;
; #pragma unroll
;             for (int i4 = 0; i4 < 4; ++i4) { const f32x4 a = *(const LAS f32x4*)(rr + 4 * i4), b = *(const LAS f32x4*)(rr + 16 + 4 * i4);
;                 xf += a.x * wf[4 * i4] + a.y * wf[4 * i4 + 1] + a.z * wf[4 * i4 + 2] + a.w * wf[4 * i4 + 3];
;                 xb += b.x * wb[4 * i4] + b.y * wb[4 * i4 + 1] + b.z * wb[4 * i4 + 2] + b.w * wb[4 * i4 + 3]; }
;             lf[pp] = logsig2(xf) * (1.f / 16.f); lb[pp] = logsig2(xb) * (1.f / 16.f);
.LBB0_423:
	s_ashr_i32 s77, s76, 31
	s_lshr_b32 s78, s77, 27
	s_add_i32 s78, s76, s78
	s_ashr_i32 s78, s78, 5
	s_mul_i32 s80, s76, 0x10400
	v_readlane_b32 s88, v253, 48
	s_mul_hi_i32 s79, s76, 0x10400
	v_readlane_b32 s89, v253, 49
	s_add_u32 s88, s88, s80
	s_addc_u32 s89, s89, s79
	s_lshr_b32 s79, s78, 30
	s_add_i32 s79, s78, s79
	s_and_b32 s79, s79, 0x1fffffc
	s_sub_i32 s78, s78, s79
	v_lshl_or_b32 v2, s78, 7, v86
	v_ashrrev_i32_e32 v3, 31, v2
	v_lshlrev_b64 v[2:3], 2, v[2:3]
	s_waitcnt lgkmcnt(0)
	v_lshl_add_u64 v[10:11], s[12:13], 0, v[2:3]
	s_movk_i32 s79, 0x1000
	v_add_co_u32_e32 v4, vcc, s79, v10
	s_movk_i32 s78, 0x2000
	s_nop 0
	v_addc_co_u32_e32 v5, vcc, 0, v11, vcc
	v_add_co_u32_e32 v6, vcc, s78, v10
	v_lshl_add_u64 v[126:127], s[16:17], 0, v[2:3]
	s_nop 0
	v_addc_co_u32_e32 v7, vcc, 0, v11, vcc
	v_add_co_u32_e32 v8, vcc, s79, v126
	s_waitcnt vmcnt(20)
	ds_write_b128 v107, v[34:37]
	s_waitcnt vmcnt(19)
	ds_write_b128 v108, v[38:41]
	s_waitcnt vmcnt(18)
	ds_write_b128 v109, v[42:45]
	s_waitcnt vmcnt(17)
	ds_write_b128 v110, v[46:49]
	s_waitcnt vmcnt(16)
	ds_write_b128 v111, v[50:53]
	v_addc_co_u32_e32 v9, vcc, 0, v127, vcc
	s_waitcnt vmcnt(15)
	ds_write_b128 v112, v[54:57] offset:8192
	s_waitcnt vmcnt(14)
	ds_write_b128 v112, v[58:61] offset:25600
	s_waitcnt vmcnt(13)
	ds_write_b128 v113, v[62:65] offset:8192
	s_waitcnt vmcnt(12)
	ds_write_b128 v113, v[66:69] offset:25600
	v_add_co_u32_e32 v16, vcc, s78, v126
	s_waitcnt lgkmcnt(0)
	s_barrier
	s_nop 0
	v_addc_co_u32_e32 v17, vcc, 0, v127, vcc
	s_movk_i32 s79, 0x3000
	global_load_dword v27, v[10:11], off
	global_load_dword v28, v[126:127], off
	global_load_dword v31, v[10:11], off offset:2048
	global_load_dword v30, v[126:127], off offset:2048
	global_load_dword v32, v[6:7], off offset:-4096
	global_load_dword v33, v[16:17], off offset:-4096
	global_load_dword v97, v[4:5], off offset:2048
	global_load_dword v96, v[8:9], off offset:2048
	global_load_dword v13, v[6:7], off
	global_load_dword v12, v[16:17], off
	global_load_dword v15, v[6:7], off offset:2048
	global_load_dword v14, v[16:17], off offset:2048
	v_add_co_u32_e32 v4, vcc, s79, v10
	s_movk_i32 s78, 0x4000
	s_nop 0
	v_addc_co_u32_e32 v5, vcc, 0, v11, vcc
	v_add_co_u32_e32 v6, vcc, s78, v10
	s_nop 1
	v_addc_co_u32_e32 v7, vcc, 0, v11, vcc
	v_add_co_u32_e32 v8, vcc, s79, v126
	global_load_dword v20, v[6:7], off offset:-4096
	s_nop 0
	v_addc_co_u32_e32 v9, vcc, 0, v127, vcc
	v_add_co_u32_e32 v22, vcc, s78, v126
	s_movk_i32 s78, 0x5000
	s_nop 0
	v_addc_co_u32_e32 v23, vcc, 0, v127, vcc
	global_load_dword v24, v[22:23], off offset:-4096
	global_load_dword v29, v[4:5], off offset:2048
	global_load_dword v26, v[8:9], off offset:2048
	global_load_dword v17, v[6:7], off
	global_load_dword v16, v[22:23], off
	global_load_dword v19, v[6:7], off offset:2048
	global_load_dword v18, v[22:23], off offset:2048
	v_add_co_u32_e32 v4, vcc, s78, v10
	s_movk_i32 s79, 0x6000
	s_nop 0
	v_addc_co_u32_e32 v5, vcc, 0, v11, vcc
	v_add_co_u32_e32 v8, vcc, s79, v10
	s_nop 1
	v_addc_co_u32_e32 v9, vcc, 0, v11, vcc
	v_add_co_u32_e32 v6, vcc, s78, v126
	s_movk_i32 s78, 0x7000
	s_nop 0
	v_addc_co_u32_e32 v7, vcc, 0, v127, vcc
	v_add_co_u32_e32 v128, vcc, s79, v126
	global_load_dword v21, v[8:9], off offset:-4096
	s_nop 0
	v_addc_co_u32_e32 v129, vcc, 0, v127, vcc
	global_load_dword v22, v[128:129], off offset:-4096
	global_load_dword v25, v[4:5], off offset:2048
	global_load_dword v23, v[6:7], off offset:2048
	s_nop 0
	global_load_dword v6, v[8:9], off
	global_load_dword v4, v[128:129], off
	s_nop 0
	global_load_dword v9, v[8:9], off offset:2048
	s_nop 0
	global_load_dword v5, v[128:129], off offset:2048
	v_add_co_u32_e32 v128, vcc, s78, v10
	s_nop 1
	v_addc_co_u32_e32 v129, vcc, 0, v11, vcc
	v_add_co_u32_e32 v126, vcc, s78, v126
	global_load_dword v10, v[128:129], off
	s_nop 0
	v_addc_co_u32_e32 v127, vcc, 0, v127, vcc
	global_load_dword v7, v[126:127], off
	global_load_dword v11, v[128:129], off offset:2048
	global_load_dword v8, v[126:127], off offset:2048
	v_lshl_add_u64 v[126:127], s[14:15], 0, v[2:3]
	global_load_dword v126, v[126:127], off
	v_lshl_add_u64 v[2:3], s[18:19], 0, v[2:3]
	global_load_dword v3, v[2:3], off
	ds_read_b128 v[136:139], v87 offset:64
	ds_read_b128 v[140:143], v87
	ds_read_b128 v[144:147], v87 offset:16
	ds_read_b128 v[148:151], v87 offset:32
	ds_read_b128 v[152:155], v87 offset:48
	s_waitcnt vmcnt(31) lgkmcnt(3)
	v_mul_f32_e32 v2, v31, v141
	s_waitcnt vmcnt(30)
	v_mul_f32_e32 v125, v30, v137
	v_fmac_f32_e32 v125, v28, v136
	s_waitcnt vmcnt(28)
	v_fmac_f32_e32 v125, v33, v138
	s_waitcnt vmcnt(26)
	v_fmac_f32_e32 v125, v96, v139
	ds_read_b128 v[136:139], v87 offset:80
	v_fmac_f32_e32 v2, v27, v140
	s_waitcnt vmcnt(23) lgkmcnt(3)
	v_mul_f32_e32 v127, v15, v145
	v_fmac_f32_e32 v2, v32, v142
	v_fmac_f32_e32 v127, v13, v144
	v_fmac_f32_e32 v2, v97, v143
	s_waitcnt vmcnt(21)
	v_fmac_f32_e32 v127, v20, v146
	s_waitcnt vmcnt(19)
	v_fmac_f32_e32 v127, v29, v147
	s_waitcnt vmcnt(1)
	v_add_f32_e32 v2, v126, v2
	v_add_f32_e32 v2, v2, v127
	s_waitcnt lgkmcnt(0)
	v_mul_f32_e32 v127, v14, v137
	v_fmac_f32_e32 v127, v12, v136
	v_fmac_f32_e32 v127, v24, v138
	s_waitcnt vmcnt(0)
	v_add_f32_e32 v125, v3, v125
	v_fmac_f32_e32 v127, v26, v139
	ds_read_b128 v[136:139], v87 offset:96
	v_add_f32_e32 v125, v125, v127
	v_mul_f32_e32 v127, v19, v149
	v_fmac_f32_e32 v127, v17, v148
	v_fmac_f32_e32 v127, v21, v150
	v_fmac_f32_e32 v127, v25, v151
	v_add_f32_e32 v2, v2, v127
	s_waitcnt lgkmcnt(0)
; #define LAS __attribute__((address_space(3)))
; __device__ __forceinline__ float logsig2(float x) { const float xc = fminf(fmaxf(x, -60.f), 60.f); return -__builtin_amdgcn_logf(1.0f + __builtin_amdgcn_exp2f(-1.4426950408889634f * xc)); }
; __device__ __forceinline__ void gla_prep_phase(LAS unsigned char* lds, const GlaPrepArgs& A, int bid, int G) {
;     ...
;         for (int pp = 0; pp < 16; ++pp) {
;             const LAS float* rr = (const LAS float*)(lds + L_R) + (pg * 16 + pp) * 32;
;             float xf = bf_, xb = bb_;
; #pragma unroll
;             for (int i4 = 0; i4 < 4; ++i4) { const f32x4 a = *(const LAS f32x4*)(rr + 4 * i4), b = *(const LAS f32x4*)(rr + 16 + 4 * i4);
;                 xf += a.x * wf[4 * i4] + a.y * wf[4 * i4 + 1] + a.z * wf[4 * i4 + 2] + a.w * wf[4 * i4 + 3];
;                 xb += b.x * wb[4 * i4] + b.y * wb[4 * i4 + 1] + b.z * wb[4 * i4 + 2] + b.w * wb[4 * i4 + 3]; }
;             lf[pp] = logsig2(xf) * (1.f / 16.f); lb[pp] = logsig2(xb) * (1.f / 16.f);
	v_mul_f32_e32 v127, v18, v137
	v_fmac_f32_e32 v127, v16, v136
	v_fmac_f32_e32 v127, v22, v138
	v_fmac_f32_e32 v127, v23, v139
	v_add_f32_e32 v125, v125, v127
	v_mul_f32_e32 v127, v9, v153
	v_fmac_f32_e32 v127, v6, v152
	v_fmac_f32_e32 v127, v10, v154
	ds_read_b128 v[136:139], v87 offset:112
	v_fmac_f32_e32 v127, v11, v155
	v_add_f32_e32 v2, v2, v127
	v_med3_f32 v2, v2, s66, v170
	v_mul_f32_e32 v2, 0xbfb8aa3b, v2
	v_exp_f32_e32 v2, v2
	s_waitcnt lgkmcnt(0)
	v_mul_f32_e32 v127, v5, v137
	v_fmac_f32_e32 v127, v4, v136
	v_fmac_f32_e32 v127, v7, v138
	v_fmac_f32_e32 v127, v8, v139
	v_add_f32_e32 v2, 1.0, v2
	ds_read_b128 v[136:139], v87 offset:128
	ds_read_b128 v[140:143], v87 offset:192
	v_log_f32_e32 v2, v2
	v_add_f32_e32 v127, v125, v127
	v_mul_f32_e32 v125, 0xbd800000, v2
	v_med3_f32 v2, v127, s66, v170
	s_waitcnt lgkmcnt(1)
	v_mul_f32_e32 v127, v31, v137
	s_waitcnt lgkmcnt(0)
	v_mul_f32_e32 v128, v30, v141
	v_fmac_f32_e32 v127, v27, v136
	v_fmac_f32_e32 v128, v28, v140
	v_fmac_f32_e32 v127, v32, v138
	v_fmac_f32_e32 v128, v33, v142
	v_fmac_f32_e32 v127, v97, v139
	v_fmac_f32_e32 v128, v96, v143
	ds_read_b128 v[136:139], v87 offset:144
	ds_read_b128 v[140:143], v87 offset:208
	v_add_f32_e32 v127, v126, v127
	v_add_f32_e32 v128, v3, v128
	v_mul_f32_e32 v2, 0xbfb8aa3b, v2
	s_waitcnt lgkmcnt(1)
	v_mul_f32_e32 v129, v15, v137
	v_fmac_f32_e32 v129, v13, v136
	v_fmac_f32_e32 v129, v20, v138
	v_fmac_f32_e32 v129, v29, v139
	v_add_f32_e32 v127, v127, v129
	s_waitcnt lgkmcnt(0)
	v_mul_f32_e32 v129, v14, v141
	v_fmac_f32_e32 v129, v12, v140
	v_fmac_f32_e32 v129, v24, v142
	v_fmac_f32_e32 v129, v26, v143
	ds_read_b128 v[136:139], v87 offset:160
	ds_read_b128 v[140:143], v87 offset:224
	v_add_f32_e32 v128, v128, v129
	v_exp_f32_e32 v2, v2
	s_waitcnt lgkmcnt(1)
	v_mul_f32_e32 v129, v19, v137
	v_fmac_f32_e32 v129, v17, v136
	v_fmac_f32_e32 v129, v21, v138
	v_fmac_f32_e32 v129, v25, v139
	v_add_f32_e32 v127, v127, v129
	s_waitcnt lgkmcnt(0)
	v_mul_f32_e32 v129, v18, v141
	v_fmac_f32_e32 v129, v16, v140
	v_fmac_f32_e32 v129, v22, v142
	v_fmac_f32_e32 v129, v23, v143
	ds_read_b128 v[136:139], v87 offset:176
	ds_read_b128 v[140:143], v87 offset:240
	v_add_f32_e32 v128, v128, v129
	v_add_f32_e32 v2, 1.0, v2
	v_log_f32_e32 v2, v2
	s_waitcnt lgkmcnt(1)
	v_mul_f32_e32 v129, v9, v137
	v_fmac_f32_e32 v129, v6, v136
	v_fmac_f32_e32 v129, v10, v138
	v_fmac_f32_e32 v129, v11, v139
	v_add_f32_e32 v127, v127, v129
	s_waitcnt lgkmcnt(0)
	v_mul_f32_e32 v129, v5, v141
	v_med3_f32 v127, v127, s66, v170
	v_fmac_f32_e32 v129, v4, v140
	v_mul_f32_e32 v127, 0xbfb8aa3b, v127
	v_fmac_f32_e32 v129, v7, v142
	v_exp_f32_e32 v127, v127
	v_fmac_f32_e32 v129, v8, v143
	ds_read_b128 v[136:139], v87 offset:256
	ds_read_b128 v[140:143], v87 offset:320
	v_add_f32_e32 v129, v128, v129
	v_add_f32_e32 v127, 1.0, v127
	v_log_f32_e32 v128, v127
	v_med3_f32 v127, v129, s66, v170
	s_waitcnt lgkmcnt(1)
	v_mul_f32_e32 v129, v31, v137
	v_fmac_f32_e32 v129, v27, v136
	s_waitcnt lgkmcnt(0)
	v_mul_f32_e32 v136, v30, v141
	v_fmac_f32_e32 v136, v28, v140
	v_fmac_f32_e32 v136, v33, v142
	v_fmac_f32_e32 v129, v32, v138
	v_fmac_f32_e32 v136, v96, v143
	v_fmac_f32_e32 v129, v97, v139
	v_add_f32_e32 v144, v3, v136
	ds_read_b128 v[136:139], v87 offset:272
	ds_read_b128 v[140:143], v87 offset:336
	v_add_f32_e32 v129, v126, v129
	v_mul_f32_e32 v127, 0xbfb8aa3b, v127
	v_exp_f32_e32 v127, v127
	s_waitcnt lgkmcnt(1)
	v_mul_f32_e32 v137, v15, v137
	v_fmac_f32_e32 v137, v13, v136
	s_waitcnt lgkmcnt(0)
	v_mul_f32_e32 v136, v14, v141
	v_fmac_f32_e32 v136, v12, v140
	v_fmac_f32_e32 v137, v20, v138
	v_fmac_f32_e32 v136, v24, v142
	v_fmac_f32_e32 v137, v29, v139
	v_fmac_f32_e32 v136, v26, v143
	v_add_f32_e32 v129, v129, v137
	v_add_f32_e32 v144, v144, v136
	ds_read_b128 v[136:139], v87 offset:288
	ds_read_b128 v[140:143], v87 offset:352
	v_add_f32_e32 v127, 1.0, v127
	v_log_f32_e32 v127, v127
	s_waitcnt lgkmcnt(1)
	v_mul_f32_e32 v137, v19, v137
	v_fmac_f32_e32 v137, v17, v136
	s_waitcnt lgkmcnt(0)
	v_mul_f32_e32 v136, v18, v141
	v_fmac_f32_e32 v136, v16, v140
	v_fmac_f32_e32 v137, v21, v138
	v_fmac_f32_e32 v136, v22, v142
	v_fmac_f32_e32 v137, v25, v139
	v_fmac_f32_e32 v136, v23, v143
	v_add_f32_e32 v129, v129, v137
	v_add_f32_e32 v144, v144, v136
	ds_read_b128 v[136:139], v87 offset:304
	ds_read_b128 v[140:143], v87 offset:368
	s_waitcnt lgkmcnt(1)
	v_mul_f32_e32 v137, v9, v137
	v_fmac_f32_e32 v137, v6, v136
	v_fmac_f32_e32 v137, v10, v138
	v_fmac_f32_e32 v137, v11, v139
	v_add_f32_e32 v129, v129, v137
	s_waitcnt lgkmcnt(0)
	v_mul_f32_e32 v136, v5, v141
	v_fmac_f32_e32 v136, v4, v140
	v_med3_f32 v129, v129, s66, v170
	v_fmac_f32_e32 v136, v7, v142
	v_mul_f32_e32 v129, 0xbfb8aa3b, v129
	v_fmac_f32_e32 v136, v8, v143
	v_exp_f32_e32 v129, v129
	v_add_f32_e32 v137, v144, v136
	ds_read_b128 v[138:141], v87 offset:384
	ds_read_b128 v[142:145], v87 offset:448
	v_add_f32_e32 v129, 1.0, v129
	v_log_f32_e32 v136, v129
	v_med3_f32 v129, v137, s66, v170
	s_waitcnt lgkmcnt(1)
	v_mul_f32_e32 v137, v31, v139
	v_fmac_f32_e32 v137, v27, v138
	s_waitcnt lgkmcnt(0)
	v_mul_f32_e32 v138, v30, v143
	v_fmac_f32_e32 v138, v28, v142
	v_fmac_f32_e32 v138, v33, v144
	v_fmac_f32_e32 v137, v32, v140
	v_fmac_f32_e32 v138, v96, v145
	v_fmac_f32_e32 v137, v97, v141
	v_add_f32_e32 v146, v3, v138
	ds_read_b128 v[138:141], v87 offset:400
	ds_read_b128 v[142:145], v87 offset:464
	v_add_f32_e32 v137, v126, v137
	v_mul_f32_e32 v129, 0xbfb8aa3b, v129
	v_exp_f32_e32 v129, v129
	s_waitcnt lgkmcnt(1)
	v_mul_f32_e32 v139, v15, v139
	v_fmac_f32_e32 v139, v13, v138
	s_waitcnt lgkmcnt(0)
; #define LAS __attribute__((address_space(3)))
; __device__ __forceinline__ float logsig2(float x) { const float xc = fminf(fmaxf(x, -60.f), 60.f); return -__builtin_amdgcn_logf(1.0f + __builtin_amdgcn_exp2f(-1.4426950408889634f * xc)); }
; __device__ __forceinline__ void gla_prep_phase(LAS unsigned char* lds, const GlaPrepArgs& A, int bid, int G) {
;     ...
;         for (int pp = 0; pp < 16; ++pp) {
;             const LAS float* rr = (const LAS float*)(lds + L_R) + (pg * 16 + pp) * 32;
;             float xf = bf_, xb = bb_;
; #pragma unroll
;             for (int i4 = 0; i4 < 4; ++i4) { const f32x4 a = *(const LAS f32x4*)(rr + 4 * i4), b = *(const LAS f32x4*)(rr + 16 + 4 * i4);
;                 xf += a.x * wf[4 * i4] + a.y * wf[4 * i4 + 1] + a.z * wf[4 * i4 + 2] + a.w * wf[4 * i4 + 3];
;                 xb += b.x * wb[4 * i4] + b.y * wb[4 * i4 + 1] + b.z * wb[4 * i4 + 2] + b.w * wb[4 * i4 + 3]; }
;             lf[pp] = logsig2(xf) * (1.f / 16.f); lb[pp] = logsig2(xb) * (1.f / 16.f);
	v_mul_f32_e32 v138, v14, v143
	v_fmac_f32_e32 v138, v12, v142
	v_fmac_f32_e32 v139, v20, v140
	v_fmac_f32_e32 v138, v24, v144
	v_fmac_f32_e32 v139, v29, v141
	v_fmac_f32_e32 v138, v26, v145
	v_add_f32_e32 v137, v137, v139
	v_add_f32_e32 v146, v146, v138
	ds_read_b128 v[138:141], v87 offset:416
	ds_read_b128 v[142:145], v87 offset:480
	v_add_f32_e32 v129, 1.0, v129
	v_log_f32_e32 v129, v129
	s_waitcnt lgkmcnt(1)
	v_mul_f32_e32 v139, v19, v139
	v_fmac_f32_e32 v139, v17, v138
	s_waitcnt lgkmcnt(0)
	v_mul_f32_e32 v138, v18, v143
	v_fmac_f32_e32 v138, v16, v142
	v_fmac_f32_e32 v139, v21, v140
	v_fmac_f32_e32 v138, v22, v144
	v_fmac_f32_e32 v139, v25, v141
	v_fmac_f32_e32 v138, v23, v145
	v_add_f32_e32 v137, v137, v139
	v_add_f32_e32 v146, v146, v138
	ds_read_b128 v[138:141], v87 offset:432
	ds_read_b128 v[142:145], v87 offset:496
	s_waitcnt lgkmcnt(1)
	v_mul_f32_e32 v139, v9, v139
	v_fmac_f32_e32 v139, v6, v138
	v_fmac_f32_e32 v139, v10, v140
	v_fmac_f32_e32 v139, v11, v141
	v_add_f32_e32 v137, v137, v139
	s_waitcnt lgkmcnt(0)
	v_mul_f32_e32 v138, v5, v143
	v_fmac_f32_e32 v138, v4, v142
	v_med3_f32 v137, v137, s66, v170
	v_fmac_f32_e32 v138, v7, v144
	v_mul_f32_e32 v137, 0xbfb8aa3b, v137
	v_fmac_f32_e32 v138, v8, v145
	v_exp_f32_e32 v137, v137
	v_add_f32_e32 v139, v146, v138
	ds_read_b128 v[140:143], v87 offset:512
	ds_read_b128 v[144:147], v87 offset:576
	v_add_f32_e32 v137, 1.0, v137
	v_log_f32_e32 v138, v137
	v_med3_f32 v137, v139, s66, v170
	s_waitcnt lgkmcnt(1)
	v_mul_f32_e32 v139, v31, v141
	v_fmac_f32_e32 v139, v27, v140
	s_waitcnt lgkmcnt(0)
	v_mul_f32_e32 v140, v30, v145
	v_fmac_f32_e32 v140, v28, v144
	v_fmac_f32_e32 v140, v33, v146
	v_fmac_f32_e32 v139, v32, v142
	v_fmac_f32_e32 v140, v96, v147
	v_fmac_f32_e32 v139, v97, v143
	v_add_f32_e32 v148, v3, v140
	ds_read_b128 v[140:143], v87 offset:528
	ds_read_b128 v[144:147], v87 offset:592
	v_add_f32_e32 v139, v126, v139
	v_mul_f32_e32 v137, 0xbfb8aa3b, v137
	v_exp_f32_e32 v137, v137
	s_waitcnt lgkmcnt(1)
	v_mul_f32_e32 v141, v15, v141
	v_fmac_f32_e32 v141, v13, v140
	s_waitcnt lgkmcnt(0)
	v_mul_f32_e32 v140, v14, v145
	v_fmac_f32_e32 v140, v12, v144
	v_fmac_f32_e32 v141, v20, v142
	v_fmac_f32_e32 v140, v24, v146
	v_fmac_f32_e32 v141, v29, v143
	v_fmac_f32_e32 v140, v26, v147
	v_add_f32_e32 v139, v139, v141
	v_add_f32_e32 v148, v148, v140
	ds_read_b128 v[140:143], v87 offset:544
	ds_read_b128 v[144:147], v87 offset:608
	v_add_f32_e32 v137, 1.0, v137
	v_log_f32_e32 v137, v137
	s_waitcnt lgkmcnt(1)
	v_mul_f32_e32 v141, v19, v141
	v_fmac_f32_e32 v141, v17, v140
	s_waitcnt lgkmcnt(0)
	v_mul_f32_e32 v140, v18, v145
	v_fmac_f32_e32 v140, v16, v144
	v_fmac_f32_e32 v141, v21, v142
	v_fmac_f32_e32 v140, v22, v146
	v_fmac_f32_e32 v141, v25, v143
	v_fmac_f32_e32 v140, v23, v147
	v_add_f32_e32 v139, v139, v141
	v_add_f32_e32 v148, v148, v140
	ds_read_b128 v[140:143], v87 offset:560
	ds_read_b128 v[144:147], v87 offset:624
	s_waitcnt lgkmcnt(1)
	v_mul_f32_e32 v141, v9, v141
	v_fmac_f32_e32 v141, v6, v140
	v_fmac_f32_e32 v141, v10, v142
	v_fmac_f32_e32 v141, v11, v143
	v_add_f32_e32 v139, v139, v141
	s_waitcnt lgkmcnt(0)
	v_mul_f32_e32 v140, v5, v145
	v_fmac_f32_e32 v140, v4, v144
	v_med3_f32 v139, v139, s66, v170
	v_fmac_f32_e32 v140, v7, v146
	v_mul_f32_e32 v139, 0xbfb8aa3b, v139
	v_fmac_f32_e32 v140, v8, v147
	v_exp_f32_e32 v139, v139
	v_add_f32_e32 v141, v148, v140
	ds_read_b128 v[142:145], v87 offset:640
	ds_read_b128 v[146:149], v87 offset:704
	v_add_f32_e32 v139, 1.0, v139
	v_log_f32_e32 v140, v139
	v_med3_f32 v139, v141, s66, v170
	s_waitcnt lgkmcnt(1)
	v_mul_f32_e32 v141, v31, v143
	v_fmac_f32_e32 v141, v27, v142
	s_waitcnt lgkmcnt(0)
	v_mul_f32_e32 v142, v30, v147
	v_fmac_f32_e32 v142, v28, v146
	v_fmac_f32_e32 v142, v33, v148
	v_fmac_f32_e32 v141, v32, v144
	v_fmac_f32_e32 v142, v96, v149
	v_fmac_f32_e32 v141, v97, v145
	v_add_f32_e32 v150, v3, v142
	ds_read_b128 v[142:145], v87 offset:656
	ds_read_b128 v[146:149], v87 offset:720
	v_add_f32_e32 v141, v126, v141
	v_mul_f32_e32 v139, 0xbfb8aa3b, v139
	v_exp_f32_e32 v139, v139
	s_waitcnt lgkmcnt(1)
	v_mul_f32_e32 v143, v15, v143
	v_fmac_f32_e32 v143, v13, v142
	s_waitcnt lgkmcnt(0)
	v_mul_f32_e32 v142, v14, v147
	v_fmac_f32_e32 v142, v12, v146
	v_fmac_f32_e32 v143, v20, v144
	v_fmac_f32_e32 v142, v24, v148
	v_fmac_f32_e32 v143, v29, v145
	v_fmac_f32_e32 v142, v26, v149
	v_add_f32_e32 v141, v141, v143
	v_add_f32_e32 v150, v150, v142
	ds_read_b128 v[142:145], v87 offset:672
	ds_read_b128 v[146:149], v87 offset:736
	v_add_f32_e32 v139, 1.0, v139
	v_log_f32_e32 v139, v139
	s_waitcnt lgkmcnt(1)
	v_mul_f32_e32 v143, v19, v143
	v_fmac_f32_e32 v143, v17, v142
	s_waitcnt lgkmcnt(0)
	v_mul_f32_e32 v142, v18, v147
	v_fmac_f32_e32 v142, v16, v146
	v_fmac_f32_e32 v143, v21, v144
	v_fmac_f32_e32 v142, v22, v148
	v_fmac_f32_e32 v143, v25, v145
	v_fmac_f32_e32 v142, v23, v149
	v_add_f32_e32 v141, v141, v143
	v_add_f32_e32 v150, v150, v142
	ds_read_b128 v[142:145], v87 offset:688
	ds_read_b128 v[146:149], v87 offset:752
	s_waitcnt lgkmcnt(1)
	v_mul_f32_e32 v143, v9, v143
	v_fmac_f32_e32 v143, v6, v142
	v_fmac_f32_e32 v143, v10, v144
	v_fmac_f32_e32 v143, v11, v145
	v_add_f32_e32 v141, v141, v143
	s_waitcnt lgkmcnt(0)
	v_mul_f32_e32 v142, v5, v147
	v_fmac_f32_e32 v142, v4, v146
	v_med3_f32 v141, v141, s66, v170
	v_fmac_f32_e32 v142, v7, v148
	v_mul_f32_e32 v141, 0xbfb8aa3b, v141
	v_fmac_f32_e32 v142, v8, v149
	v_exp_f32_e32 v141, v141
	v_add_f32_e32 v143, v150, v142
	ds_read_b128 v[144:147], v87 offset:768
	ds_read_b128 v[148:151], v87 offset:832
	v_add_f32_e32 v141, 1.0, v141
	v_log_f32_e32 v142, v141
	v_med3_f32 v141, v143, s66, v170
	s_waitcnt lgkmcnt(1)
; #define LAS __attribute__((address_space(3)))
; __device__ __forceinline__ float logsig2(float x) { const float xc = fminf(fmaxf(x, -60.f), 60.f); return -__builtin_amdgcn_logf(1.0f + __builtin_amdgcn_exp2f(-1.4426950408889634f * xc)); }
; __device__ __forceinline__ void gla_prep_phase(LAS unsigned char* lds, const GlaPrepArgs& A, int bid, int G) {
;     ...
;         for (int pp = 0; pp < 16; ++pp) {
;             const LAS float* rr = (const LAS float*)(lds + L_R) + (pg * 16 + pp) * 32;
;             float xf = bf_, xb = bb_;
; #pragma unroll
;             for (int i4 = 0; i4 < 4; ++i4) { const f32x4 a = *(const LAS f32x4*)(rr + 4 * i4), b = *(const LAS f32x4*)(rr + 16 + 4 * i4);
;                 xf += a.x * wf[4 * i4] + a.y * wf[4 * i4 + 1] + a.z * wf[4 * i4 + 2] + a.w * wf[4 * i4 + 3];
;                 xb += b.x * wb[4 * i4] + b.y * wb[4 * i4 + 1] + b.z * wb[4 * i4 + 2] + b.w * wb[4 * i4 + 3]; }
;             lf[pp] = logsig2(xf) * (1.f / 16.f); lb[pp] = logsig2(xb) * (1.f / 16.f);
;         }
	v_mul_f32_e32 v143, v31, v145
	v_fmac_f32_e32 v143, v27, v144
	s_waitcnt lgkmcnt(0)
	v_mul_f32_e32 v144, v30, v149
	v_fmac_f32_e32 v144, v28, v148
	v_fmac_f32_e32 v144, v33, v150
	v_fmac_f32_e32 v143, v32, v146
	v_fmac_f32_e32 v144, v96, v151
	v_fmac_f32_e32 v143, v97, v147
	v_add_f32_e32 v152, v3, v144
	ds_read_b128 v[144:147], v87 offset:784
	ds_read_b128 v[148:151], v87 offset:848
	v_add_f32_e32 v143, v126, v143
	v_mul_f32_e32 v141, 0xbfb8aa3b, v141
	v_exp_f32_e32 v141, v141
	s_waitcnt lgkmcnt(1)
	v_mul_f32_e32 v145, v15, v145
	v_fmac_f32_e32 v145, v13, v144
	s_waitcnt lgkmcnt(0)
	v_mul_f32_e32 v144, v14, v149
	v_fmac_f32_e32 v144, v12, v148
	v_fmac_f32_e32 v145, v20, v146
	v_fmac_f32_e32 v144, v24, v150
	v_fmac_f32_e32 v145, v29, v147
	v_fmac_f32_e32 v144, v26, v151
	v_add_f32_e32 v143, v143, v145
	v_add_f32_e32 v152, v152, v144
	ds_read_b128 v[144:147], v87 offset:800
	ds_read_b128 v[148:151], v87 offset:864
	v_add_f32_e32 v141, 1.0, v141
	v_log_f32_e32 v141, v141
	s_waitcnt lgkmcnt(1)
	v_mul_f32_e32 v145, v19, v145
	v_fmac_f32_e32 v145, v17, v144
	s_waitcnt lgkmcnt(0)
	v_mul_f32_e32 v144, v18, v149
	v_fmac_f32_e32 v144, v16, v148
	v_fmac_f32_e32 v145, v21, v146
	v_fmac_f32_e32 v144, v22, v150
	v_fmac_f32_e32 v145, v25, v147
	v_fmac_f32_e32 v144, v23, v151
	v_add_f32_e32 v143, v143, v145
	v_add_f32_e32 v152, v152, v144
	ds_read_b128 v[144:147], v87 offset:816
	ds_read_b128 v[148:151], v87 offset:880
	s_waitcnt lgkmcnt(1)
	v_mul_f32_e32 v145, v9, v145
	v_fmac_f32_e32 v145, v6, v144
	v_fmac_f32_e32 v145, v10, v146
	v_fmac_f32_e32 v145, v11, v147
	v_add_f32_e32 v143, v143, v145
	s_waitcnt lgkmcnt(0)
	v_mul_f32_e32 v144, v5, v149
	v_fmac_f32_e32 v144, v4, v148
	v_med3_f32 v143, v143, s66, v170
	v_fmac_f32_e32 v144, v7, v150
	v_mul_f32_e32 v143, 0xbfb8aa3b, v143
	v_fmac_f32_e32 v144, v8, v151
	v_exp_f32_e32 v143, v143
	v_add_f32_e32 v145, v152, v144
	ds_read_b128 v[146:149], v87 offset:896
	ds_read_b128 v[150:153], v87 offset:960
	v_add_f32_e32 v143, 1.0, v143
	v_log_f32_e32 v144, v143
	v_med3_f32 v143, v145, s66, v170
	s_waitcnt lgkmcnt(1)
	v_mul_f32_e32 v145, v31, v147
	v_fmac_f32_e32 v145, v27, v146
	s_waitcnt lgkmcnt(0)
	v_mul_f32_e32 v146, v30, v151
	v_fmac_f32_e32 v146, v28, v150
	v_fmac_f32_e32 v146, v33, v152
	v_fmac_f32_e32 v145, v32, v148
	v_fmac_f32_e32 v146, v96, v153
	v_fmac_f32_e32 v145, v97, v149
	v_add_f32_e32 v154, v3, v146
	ds_read_b128 v[146:149], v87 offset:912
	ds_read_b128 v[150:153], v87 offset:976
	v_add_f32_e32 v145, v126, v145
	v_mul_f32_e32 v143, 0xbfb8aa3b, v143
	v_exp_f32_e32 v143, v143
	s_waitcnt lgkmcnt(1)
	v_mul_f32_e32 v147, v15, v147
	v_fmac_f32_e32 v147, v13, v146
	s_waitcnt lgkmcnt(0)
	v_mul_f32_e32 v146, v14, v151
	v_fmac_f32_e32 v146, v12, v150
	v_fmac_f32_e32 v147, v20, v148
	v_fmac_f32_e32 v146, v24, v152
	v_fmac_f32_e32 v147, v29, v149
	v_fmac_f32_e32 v146, v26, v153
	v_add_f32_e32 v145, v145, v147
	v_add_f32_e32 v154, v154, v146
	ds_read_b128 v[146:149], v87 offset:928
	ds_read_b128 v[150:153], v87 offset:992
	v_add_f32_e32 v143, 1.0, v143
	v_log_f32_e32 v143, v143
	s_waitcnt lgkmcnt(1)
	v_mul_f32_e32 v147, v19, v147
	v_fmac_f32_e32 v147, v17, v146
	s_waitcnt lgkmcnt(0)
	v_mul_f32_e32 v146, v18, v151
	v_fmac_f32_e32 v146, v16, v150
	v_fmac_f32_e32 v147, v21, v148
	v_fmac_f32_e32 v146, v22, v152
	v_fmac_f32_e32 v147, v25, v149
	v_fmac_f32_e32 v146, v23, v153
	v_add_f32_e32 v145, v145, v147
	v_add_f32_e32 v154, v154, v146
	ds_read_b128 v[146:149], v87 offset:944
	ds_read_b128 v[150:153], v87 offset:1008
	s_waitcnt lgkmcnt(1)
	v_mul_f32_e32 v147, v9, v147
	v_fmac_f32_e32 v147, v6, v146
	v_fmac_f32_e32 v147, v10, v148
	v_fmac_f32_e32 v147, v11, v149
	v_add_f32_e32 v145, v145, v147
	s_waitcnt lgkmcnt(0)
	v_mul_f32_e32 v146, v5, v151
	v_fmac_f32_e32 v146, v4, v150
	v_med3_f32 v145, v145, s66, v170
	v_fmac_f32_e32 v146, v7, v152
	v_mul_f32_e32 v145, 0xbfb8aa3b, v145
	v_fmac_f32_e32 v146, v8, v153
	v_exp_f32_e32 v145, v145
	v_add_f32_e32 v147, v154, v146
	ds_read_b128 v[148:151], v87 offset:1024
	ds_read_b128 v[152:155], v87 offset:1088
	v_add_f32_e32 v145, 1.0, v145
	v_log_f32_e32 v146, v145
	v_med3_f32 v145, v147, s66, v170
	s_waitcnt lgkmcnt(1)
	v_mul_f32_e32 v147, v31, v149
	v_fmac_f32_e32 v147, v27, v148
	s_waitcnt lgkmcnt(0)
	v_mul_f32_e32 v148, v30, v153
	v_fmac_f32_e32 v148, v28, v152
	v_fmac_f32_e32 v148, v33, v154
	v_fmac_f32_e32 v147, v32, v150
	v_fmac_f32_e32 v148, v96, v155
	v_fmac_f32_e32 v147, v97, v151
	v_add_f32_e32 v156, v3, v148
	ds_read_b128 v[148:151], v87 offset:1040
	ds_read_b128 v[152:155], v87 offset:1104
	v_add_f32_e32 v147, v126, v147
	v_mul_f32_e32 v145, 0xbfb8aa3b, v145
	v_exp_f32_e32 v145, v145
	s_waitcnt lgkmcnt(1)
	v_mul_f32_e32 v149, v15, v149
	v_fmac_f32_e32 v149, v13, v148
	s_waitcnt lgkmcnt(0)
	v_mul_f32_e32 v148, v14, v153
	v_fmac_f32_e32 v148, v12, v152
	v_fmac_f32_e32 v149, v20, v150
	v_fmac_f32_e32 v148, v24, v154
	v_fmac_f32_e32 v149, v29, v151
	v_fmac_f32_e32 v148, v26, v155
	v_add_f32_e32 v147, v147, v149
	v_add_f32_e32 v156, v156, v148
	ds_read_b128 v[148:151], v87 offset:1056
	ds_read_b128 v[152:155], v87 offset:1120
	v_add_f32_e32 v145, 1.0, v145
	v_log_f32_e32 v145, v145
	s_waitcnt lgkmcnt(1)
	v_mul_f32_e32 v149, v19, v149
	v_fmac_f32_e32 v149, v17, v148
	s_waitcnt lgkmcnt(0)
	v_mul_f32_e32 v148, v18, v153
	v_fmac_f32_e32 v148, v16, v152
	v_fmac_f32_e32 v149, v21, v150
	v_fmac_f32_e32 v148, v22, v154
	v_fmac_f32_e32 v149, v25, v151
	v_fmac_f32_e32 v148, v23, v155
	v_add_f32_e32 v147, v147, v149
	v_add_f32_e32 v156, v156, v148
	ds_read_b128 v[148:151], v87 offset:1072
	ds_read_b128 v[152:155], v87 offset:1136
	s_waitcnt lgkmcnt(1)
; #define LAS __attribute__((address_space(3)))
; __device__ __forceinline__ float logsig2(float x) { const float xc = fminf(fmaxf(x, -60.f), 60.f); return -__builtin_amdgcn_logf(1.0f + __builtin_amdgcn_exp2f(-1.4426950408889634f * xc)); }
; __device__ __forceinline__ void gla_prep_phase(LAS unsigned char* lds, const GlaPrepArgs& A, int bid, int G) {
;     ...
;         for (int pp = 0; pp < 16; ++pp) {
;             const LAS float* rr = (const LAS float*)(lds + L_R) + (pg * 16 + pp) * 32;
;             float xf = bf_, xb = bb_;
; #pragma unroll
;             for (int i4 = 0; i4 < 4; ++i4) { const f32x4 a = *(const LAS f32x4*)(rr + 4 * i4), b = *(const LAS f32x4*)(rr + 16 + 4 * i4);
;                 xf += a.x * wf[4 * i4] + a.y * wf[4 * i4 + 1] + a.z * wf[4 * i4 + 2] + a.w * wf[4 * i4 + 3];
;                 xb += b.x * wb[4 * i4] + b.y * wb[4 * i4 + 1] + b.z * wb[4 * i4 + 2] + b.w * wb[4 * i4 + 3]; }
;             lf[pp] = logsig2(xf) * (1.f / 16.f); lb[pp] = logsig2(xb) * (1.f / 16.f);
;         }
	v_mul_f32_e32 v149, v9, v149
	v_fmac_f32_e32 v149, v6, v148
	v_fmac_f32_e32 v149, v10, v150
	v_fmac_f32_e32 v149, v11, v151
	v_add_f32_e32 v147, v147, v149
	s_waitcnt lgkmcnt(0)
	v_mul_f32_e32 v148, v5, v153
	v_fmac_f32_e32 v148, v4, v152
	v_med3_f32 v147, v147, s66, v170
	v_fmac_f32_e32 v148, v7, v154
	v_mul_f32_e32 v147, 0xbfb8aa3b, v147
	v_fmac_f32_e32 v148, v8, v155
	v_exp_f32_e32 v147, v147
	v_add_f32_e32 v149, v156, v148
	ds_read_b128 v[150:153], v87 offset:1152
	ds_read_b128 v[154:157], v87 offset:1216
	v_add_f32_e32 v147, 1.0, v147
	v_log_f32_e32 v148, v147
	v_med3_f32 v147, v149, s66, v170
	s_waitcnt lgkmcnt(1)
	v_mul_f32_e32 v149, v31, v151
	v_fmac_f32_e32 v149, v27, v150
	s_waitcnt lgkmcnt(0)
	v_mul_f32_e32 v150, v30, v155
	v_fmac_f32_e32 v150, v28, v154
	v_fmac_f32_e32 v150, v33, v156
	v_fmac_f32_e32 v149, v32, v152
	v_fmac_f32_e32 v150, v96, v157
	v_fmac_f32_e32 v149, v97, v153
	v_add_f32_e32 v158, v3, v150
	ds_read_b128 v[150:153], v87 offset:1168
	ds_read_b128 v[154:157], v87 offset:1232
	v_add_f32_e32 v149, v126, v149
	v_mul_f32_e32 v147, 0xbfb8aa3b, v147
	v_exp_f32_e32 v147, v147
	s_waitcnt lgkmcnt(1)
	v_mul_f32_e32 v151, v15, v151
	v_fmac_f32_e32 v151, v13, v150
	s_waitcnt lgkmcnt(0)
	v_mul_f32_e32 v150, v14, v155
	v_fmac_f32_e32 v150, v12, v154
	v_fmac_f32_e32 v151, v20, v152
	v_fmac_f32_e32 v150, v24, v156
	v_fmac_f32_e32 v151, v29, v153
	v_fmac_f32_e32 v150, v26, v157
	v_add_f32_e32 v149, v149, v151
	v_add_f32_e32 v158, v158, v150
	ds_read_b128 v[150:153], v87 offset:1184
	ds_read_b128 v[154:157], v87 offset:1248
	v_add_f32_e32 v147, 1.0, v147
	v_log_f32_e32 v147, v147
	s_waitcnt lgkmcnt(1)
	v_mul_f32_e32 v151, v19, v151
	v_fmac_f32_e32 v151, v17, v150
	s_waitcnt lgkmcnt(0)
	v_mul_f32_e32 v150, v18, v155
	v_fmac_f32_e32 v150, v16, v154
	v_fmac_f32_e32 v151, v21, v152
	v_fmac_f32_e32 v150, v22, v156
	v_fmac_f32_e32 v151, v25, v153
	v_fmac_f32_e32 v150, v23, v157
	v_add_f32_e32 v149, v149, v151
	v_add_f32_e32 v158, v158, v150
	ds_read_b128 v[150:153], v87 offset:1200
	ds_read_b128 v[154:157], v87 offset:1264
	s_waitcnt lgkmcnt(1)
	v_mul_f32_e32 v151, v9, v151
	v_fmac_f32_e32 v151, v6, v150
	s_waitcnt lgkmcnt(0)
	v_mul_f32_e32 v150, v5, v155
	v_fmac_f32_e32 v150, v4, v154
	v_fmac_f32_e32 v150, v7, v156
	v_fmac_f32_e32 v151, v10, v152
	v_fmac_f32_e32 v150, v8, v157
	v_fmac_f32_e32 v151, v11, v153
	v_add_f32_e32 v150, v158, v150
	ds_read_b128 v[152:155], v87 offset:1280
	ds_read_b128 v[156:159], v87 offset:1344
	v_add_f32_e32 v149, v149, v151
	v_med3_f32 v150, v150, s66, v170
	v_mul_f32_e32 v150, 0xbfb8aa3b, v150
	s_waitcnt lgkmcnt(1)
	v_mul_f32_e32 v151, v31, v153
	v_fmac_f32_e32 v151, v27, v152
	s_waitcnt lgkmcnt(0)
	v_mul_f32_e32 v152, v30, v157
	v_fmac_f32_e32 v152, v28, v156
	v_fmac_f32_e32 v152, v33, v158
	v_fmac_f32_e32 v151, v32, v154
	v_fmac_f32_e32 v152, v96, v159
	v_fmac_f32_e32 v151, v97, v155
	v_add_f32_e32 v160, v3, v152
	ds_read_b128 v[152:155], v87 offset:1296
	ds_read_b128 v[156:159], v87 offset:1360
	v_add_f32_e32 v151, v126, v151
	v_med3_f32 v149, v149, s66, v170
	v_exp_f32_e32 v150, v150
	s_waitcnt lgkmcnt(1)
	v_mul_f32_e32 v153, v15, v153
	v_fmac_f32_e32 v153, v13, v152
	s_waitcnt lgkmcnt(0)
	v_mul_f32_e32 v152, v14, v157
	v_fmac_f32_e32 v152, v12, v156
	v_fmac_f32_e32 v153, v20, v154
	v_fmac_f32_e32 v152, v24, v158
	v_fmac_f32_e32 v153, v29, v155
	v_fmac_f32_e32 v152, v26, v159
	v_add_f32_e32 v151, v151, v153
	v_add_f32_e32 v160, v160, v152
	ds_read_b128 v[152:155], v87 offset:1312
	ds_read_b128 v[156:159], v87 offset:1376
	v_mul_f32_e32 v149, 0xbfb8aa3b, v149
	v_exp_f32_e32 v149, v149
	v_add_f32_e32 v150, 1.0, v150
	s_waitcnt lgkmcnt(1)
	v_mul_f32_e32 v153, v19, v153
	v_fmac_f32_e32 v153, v17, v152
	s_waitcnt lgkmcnt(0)
	v_mul_f32_e32 v152, v18, v157
	v_fmac_f32_e32 v152, v16, v156
	v_fmac_f32_e32 v153, v21, v154
	v_fmac_f32_e32 v152, v22, v158
	v_fmac_f32_e32 v153, v25, v155
	v_fmac_f32_e32 v152, v23, v159
	v_add_f32_e32 v151, v151, v153
	v_add_f32_e32 v160, v160, v152
	ds_read_b128 v[152:155], v87 offset:1328
	ds_read_b128 v[156:159], v87 offset:1392
	v_log_f32_e32 v150, v150
	v_add_f32_e32 v149, 1.0, v149
	v_log_f32_e32 v149, v149
	s_waitcnt lgkmcnt(1)
	v_mul_f32_e32 v153, v9, v153
	v_fmac_f32_e32 v153, v6, v152
	s_waitcnt lgkmcnt(0)
	v_mul_f32_e32 v152, v5, v157
	v_fmac_f32_e32 v152, v4, v156
	v_fmac_f32_e32 v152, v7, v158
	v_fmac_f32_e32 v153, v10, v154
	v_fmac_f32_e32 v152, v8, v159
	v_fmac_f32_e32 v153, v11, v155
	v_add_f32_e32 v152, v160, v152
	ds_read_b128 v[154:157], v87 offset:1408
	ds_read_b128 v[158:161], v87 offset:1472
	v_add_f32_e32 v151, v151, v153
	v_med3_f32 v152, v152, s66, v170
	v_mul_f32_e32 v152, 0xbfb8aa3b, v152
	s_waitcnt lgkmcnt(1)
	v_mul_f32_e32 v153, v31, v155
	v_fmac_f32_e32 v153, v27, v154
	s_waitcnt lgkmcnt(0)
	v_mul_f32_e32 v154, v30, v159
	v_fmac_f32_e32 v154, v28, v158
	v_fmac_f32_e32 v154, v33, v160
	v_fmac_f32_e32 v153, v32, v156
	v_fmac_f32_e32 v154, v96, v161
	v_fmac_f32_e32 v153, v97, v157
	v_add_f32_e32 v162, v3, v154
	ds_read_b128 v[154:157], v87 offset:1424
	ds_read_b128 v[158:161], v87 offset:1488
	v_add_f32_e32 v153, v126, v153
	v_exp_f32_e32 v152, v152
	v_med3_f32 v151, v151, s66, v170
	s_waitcnt lgkmcnt(1)
	v_mul_f32_e32 v155, v15, v155
	v_fmac_f32_e32 v155, v13, v154
	s_waitcnt lgkmcnt(0)
	v_mul_f32_e32 v154, v14, v159
	v_fmac_f32_e32 v154, v12, v158
	v_fmac_f32_e32 v155, v20, v156
	v_fmac_f32_e32 v154, v24, v160
	v_fmac_f32_e32 v155, v29, v157
	v_fmac_f32_e32 v154, v26, v161
	v_add_f32_e32 v153, v153, v155
	v_add_f32_e32 v162, v162, v154
	ds_read_b128 v[154:157], v87 offset:1440
	ds_read_b128 v[158:161], v87 offset:1504
	v_mul_f32_e32 v151, 0xbfb8aa3b, v151
	v_exp_f32_e32 v151, v151
	v_add_f32_e32 v152, 1.0, v152
	s_waitcnt lgkmcnt(1)
; #define LAS __attribute__((address_space(3)))
; __device__ __forceinline__ float logsig2(float x) { const float xc = fminf(fmaxf(x, -60.f), 60.f); return -__builtin_amdgcn_logf(1.0f + __builtin_amdgcn_exp2f(-1.4426950408889634f * xc)); }
; __device__ __forceinline__ void gla_prep_phase(LAS unsigned char* lds, const GlaPrepArgs& A, int bid, int G) {
;     ...
;         for (int pp = 0; pp < 16; ++pp) {
;             const LAS float* rr = (const LAS float*)(lds + L_R) + (pg * 16 + pp) * 32;
;             float xf = bf_, xb = bb_;
; #pragma unroll
;             for (int i4 = 0; i4 < 4; ++i4) { const f32x4 a = *(const LAS f32x4*)(rr + 4 * i4), b = *(const LAS f32x4*)(rr + 16 + 4 * i4);
;                 xf += a.x * wf[4 * i4] + a.y * wf[4 * i4 + 1] + a.z * wf[4 * i4 + 2] + a.w * wf[4 * i4 + 3];
;                 xb += b.x * wb[4 * i4] + b.y * wb[4 * i4 + 1] + b.z * wb[4 * i4 + 2] + b.w * wb[4 * i4 + 3]; }
;             lf[pp] = logsig2(xf) * (1.f / 16.f); lb[pp] = logsig2(xb) * (1.f / 16.f);
;         }
	v_mul_f32_e32 v155, v19, v155
	v_fmac_f32_e32 v155, v17, v154
	s_waitcnt lgkmcnt(0)
	v_mul_f32_e32 v154, v18, v159
	v_fmac_f32_e32 v154, v16, v158
	v_fmac_f32_e32 v155, v21, v156
	v_fmac_f32_e32 v154, v22, v160
	v_fmac_f32_e32 v155, v25, v157
	v_fmac_f32_e32 v154, v23, v161
	v_add_f32_e32 v153, v153, v155
	v_add_f32_e32 v162, v162, v154
	ds_read_b128 v[154:157], v87 offset:1456
	ds_read_b128 v[158:161], v87 offset:1520
	v_log_f32_e32 v152, v152
	v_add_f32_e32 v151, 1.0, v151
	v_log_f32_e32 v151, v151
	s_waitcnt lgkmcnt(1)
	v_mul_f32_e32 v155, v9, v155
	v_fmac_f32_e32 v155, v6, v154
	s_waitcnt lgkmcnt(0)
	v_mul_f32_e32 v154, v5, v159
	v_fmac_f32_e32 v154, v4, v158
	v_fmac_f32_e32 v154, v7, v160
	v_fmac_f32_e32 v155, v10, v156
	v_fmac_f32_e32 v154, v8, v161
	v_fmac_f32_e32 v155, v11, v157
	v_add_f32_e32 v154, v162, v154
	ds_read_b128 v[156:159], v87 offset:1536
	ds_read_b128 v[160:163], v87 offset:1600
	v_add_f32_e32 v153, v153, v155
	v_med3_f32 v154, v154, s66, v170
	v_mul_f32_e32 v154, 0xbfb8aa3b, v154
	s_waitcnt lgkmcnt(1)
	v_mul_f32_e32 v155, v31, v157
	v_fmac_f32_e32 v155, v27, v156
	s_waitcnt lgkmcnt(0)
	v_mul_f32_e32 v156, v30, v161
	v_fmac_f32_e32 v156, v28, v160
	v_fmac_f32_e32 v156, v33, v162
	v_fmac_f32_e32 v155, v32, v158
	v_fmac_f32_e32 v156, v96, v163
	v_fmac_f32_e32 v155, v97, v159
	v_add_f32_e32 v173, v3, v156
	ds_read_b128 v[156:159], v87 offset:1552
	ds_read_b128 v[160:163], v87 offset:1616
	v_add_f32_e32 v155, v126, v155
	v_exp_f32_e32 v154, v154
	v_med3_f32 v153, v153, s66, v170
	s_waitcnt lgkmcnt(1)
	v_mul_f32_e32 v157, v15, v157
	v_fmac_f32_e32 v157, v13, v156
	s_waitcnt lgkmcnt(0)
	v_mul_f32_e32 v156, v14, v161
	v_fmac_f32_e32 v156, v12, v160
	v_fmac_f32_e32 v157, v20, v158
	v_fmac_f32_e32 v156, v24, v162
	v_fmac_f32_e32 v157, v29, v159
	v_fmac_f32_e32 v156, v26, v163
	v_add_f32_e32 v155, v155, v157
	v_add_f32_e32 v173, v173, v156
	ds_read_b128 v[156:159], v87 offset:1568
	ds_read_b128 v[160:163], v87 offset:1632
	v_add_f32_e32 v154, 1.0, v154
	v_mul_f32_e32 v153, 0xbfb8aa3b, v153
	v_log_f32_e32 v154, v154
	s_waitcnt lgkmcnt(1)
	v_mul_f32_e32 v157, v19, v157
	v_fmac_f32_e32 v157, v17, v156
	s_waitcnt lgkmcnt(0)
	v_mul_f32_e32 v156, v18, v161
	v_fmac_f32_e32 v156, v16, v160
	v_fmac_f32_e32 v157, v21, v158
	v_fmac_f32_e32 v156, v22, v162
	v_fmac_f32_e32 v157, v25, v159
	v_fmac_f32_e32 v156, v23, v163
	v_add_f32_e32 v155, v155, v157
	v_add_f32_e32 v173, v173, v156
	ds_read_b128 v[156:159], v87 offset:1584
	ds_read_b128 v[160:163], v87 offset:1648
	v_exp_f32_e32 v153, v153
	s_waitcnt lgkmcnt(1)
	v_mul_f32_e32 v157, v9, v157
	v_fmac_f32_e32 v157, v6, v156
	v_fmac_f32_e32 v157, v10, v158
	s_waitcnt lgkmcnt(0)
	v_mul_f32_e32 v156, v5, v161
	v_fmac_f32_e32 v157, v11, v159
	v_fmac_f32_e32 v156, v4, v160
	ds_read_b128 v[158:161], v87 offset:1664
	ds_read_b128 v[174:177], v87 offset:1728
	v_add_f32_e32 v155, v155, v157
	v_fmac_f32_e32 v156, v7, v162
	v_fmac_f32_e32 v156, v8, v163
	s_waitcnt lgkmcnt(1)
	v_mul_f32_e32 v157, v31, v159
	v_fmac_f32_e32 v157, v27, v158
	s_waitcnt lgkmcnt(0)
	v_mul_f32_e32 v158, v30, v175
	v_fmac_f32_e32 v158, v28, v174
	v_fmac_f32_e32 v158, v33, v176
	v_fmac_f32_e32 v157, v32, v160
	v_fmac_f32_e32 v158, v96, v177
	v_fmac_f32_e32 v157, v97, v161
	v_add_f32_e32 v162, v3, v158
	ds_read_b128 v[158:161], v87 offset:1680
	ds_read_b128 v[174:177], v87 offset:1744
	v_add_f32_e32 v157, v126, v157
	v_add_f32_e32 v156, v173, v156
	v_med3_f32 v156, v156, s66, v170
	s_waitcnt lgkmcnt(1)
	v_mul_f32_e32 v159, v15, v159
	v_fmac_f32_e32 v159, v13, v158
	s_waitcnt lgkmcnt(0)
	v_mul_f32_e32 v158, v14, v175
	v_fmac_f32_e32 v158, v12, v174
	v_fmac_f32_e32 v159, v20, v160
	v_fmac_f32_e32 v158, v24, v176
	v_fmac_f32_e32 v159, v29, v161
	v_fmac_f32_e32 v158, v26, v177
	v_add_f32_e32 v157, v157, v159
	v_add_f32_e32 v162, v162, v158
	ds_read_b128 v[158:161], v87 offset:1696
	ds_read_b128 v[174:177], v87 offset:1760
	v_mul_f32_e32 v156, 0xbfb8aa3b, v156
	v_exp_f32_e32 v156, v156
	v_med3_f32 v155, v155, s66, v170
	s_waitcnt lgkmcnt(1)
	v_mul_f32_e32 v159, v19, v159
	v_fmac_f32_e32 v159, v17, v158
	s_waitcnt lgkmcnt(0)
	v_mul_f32_e32 v158, v18, v175
	v_fmac_f32_e32 v158, v16, v174
	v_fmac_f32_e32 v159, v21, v160
	v_fmac_f32_e32 v158, v22, v176
	v_fmac_f32_e32 v159, v25, v161
	v_fmac_f32_e32 v158, v23, v177
	v_add_f32_e32 v157, v157, v159
	v_add_f32_e32 v162, v162, v158
	ds_read_b128 v[158:161], v87 offset:1712
	ds_read_b128 v[174:177], v87 offset:1776
	v_add_f32_e32 v156, 1.0, v156
	v_log_f32_e32 v156, v156
	v_mul_f32_e32 v155, 0xbfb8aa3b, v155
	s_waitcnt lgkmcnt(1)
	v_mul_f32_e32 v159, v9, v159
	v_fmac_f32_e32 v159, v6, v158
	s_waitcnt lgkmcnt(0)
	v_mul_f32_e32 v158, v5, v175
	v_fmac_f32_e32 v158, v4, v174
	v_fmac_f32_e32 v158, v7, v176
	v_fmac_f32_e32 v159, v10, v160
	v_fmac_f32_e32 v158, v8, v177
	v_fmac_f32_e32 v159, v11, v161
	v_add_f32_e32 v158, v162, v158
	ds_read_b128 v[160:163], v87 offset:1792
	ds_read_b128 v[174:177], v87 offset:1856
	v_add_f32_e32 v157, v157, v159
	v_med3_f32 v158, v158, s66, v170
	v_mul_f32_e32 v158, 0xbfb8aa3b, v158
	s_waitcnt lgkmcnt(1)
	v_mul_f32_e32 v159, v31, v161
	v_fmac_f32_e32 v159, v27, v160
	s_waitcnt lgkmcnt(0)
	v_mul_f32_e32 v160, v30, v175
	v_fmac_f32_e32 v160, v28, v174
	v_fmac_f32_e32 v160, v33, v176
	v_fmac_f32_e32 v159, v32, v162
	v_fmac_f32_e32 v160, v96, v177
	v_fmac_f32_e32 v159, v97, v163
	v_add_f32_e32 v173, v3, v160
	ds_read_b128 v[160:163], v87 offset:1808
	ds_read_b128 v[174:177], v87 offset:1872
	v_add_f32_e32 v159, v126, v159
	v_exp_f32_e32 v158, v158
	v_med3_f32 v157, v157, s66, v170
	s_waitcnt lgkmcnt(1)
	v_mul_f32_e32 v161, v15, v161
	v_fmac_f32_e32 v161, v13, v160
	s_waitcnt lgkmcnt(0)
; #define LAS __attribute__((address_space(3)))
; #define LBAR() do { asm volatile("s_waitcnt lgkmcnt(0)" ::: "memory"); __builtin_amdgcn_s_barrier(); asm volatile("" ::: "memory"); } while (0)
; __device__ __forceinline__ float logsig2(float x) { const float xc = fminf(fmaxf(x, -60.f), 60.f); return -__builtin_amdgcn_logf(1.0f + __builtin_amdgcn_exp2f(-1.4426950408889634f * xc)); }
; __device__ __forceinline__ void gla_prep_phase(LAS unsigned char* lds, const GlaPrepArgs& A, int bid, int G) {
;     ...
;         for (int pp = 0; pp < 16; ++pp) {
;             const LAS float* rr = (const LAS float*)(lds + L_R) + (pg * 16 + pp) * 32;
;             float xf = bf_, xb = bb_;
; #pragma unroll
;             for (int i4 = 0; i4 < 4; ++i4) { const f32x4 a = *(const LAS f32x4*)(rr + 4 * i4), b = *(const LAS f32x4*)(rr + 16 + 4 * i4);
;                 xf += a.x * wf[4 * i4] + a.y * wf[4 * i4 + 1] + a.z * wf[4 * i4 + 2] + a.w * wf[4 * i4 + 3];
;                 xb += b.x * wb[4 * i4] + b.y * wb[4 * i4 + 1] + b.z * wb[4 * i4 + 2] + b.w * wb[4 * i4 + 3]; }
;             lf[pp] = logsig2(xf) * (1.f / 16.f); lb[pp] = logsig2(xb) * (1.f / 16.f);
;         }
; #pragma unroll
;         for (int pp = 1; pp < 16; ++pp) lf[pp] += lf[pp - 1];
; #pragma unroll
;     ...
;         LAS float* tot = (LAS float*)(lds + L_TOT);
;         tot[pg * 128 + dd] = lf[15]; tot[512 + pg * 128 + dd] = lb[0];
;         LBAR();
;         float offf = 0.f, offb = 0.f, glf = 0.f, glb = 0.f;
; #pragma unroll
;         for (int g = 0; g < 4; ++g) { const float tf = tot[g * 128 + dd], tb = tot[512 + g * 128 + dd]; glf += tf; glb += tb; if (g < pg) offf += tf; if (g > pg) offb += tb; }
;         const float eglf = __builtin_amdgcn_exp2f(glf), eglb = __builtin_amdgcn_exp2f(glb);
;         if (pg == 0) { float* sc = (float*)(blob + B_SC); sc[dd] = eglf; sc[128 + dd] = eglb; }
	v_mul_f32_e32 v160, v14, v175
	v_fmac_f32_e32 v160, v12, v174
	v_fmac_f32_e32 v161, v20, v162
	v_fmac_f32_e32 v160, v24, v176
	v_fmac_f32_e32 v161, v29, v163
	v_fmac_f32_e32 v160, v26, v177
	v_add_f32_e32 v159, v159, v161
	v_add_f32_e32 v173, v173, v160
	ds_read_b128 v[160:163], v87 offset:1824
	ds_read_b128 v[174:177], v87 offset:1888
	v_add_f32_e32 v158, 1.0, v158
	v_log_f32_e32 v158, v158
	v_exp_f32_e32 v155, v155
	s_waitcnt lgkmcnt(1)
	v_mul_f32_e32 v161, v19, v161
	v_fmac_f32_e32 v161, v17, v160
	s_waitcnt lgkmcnt(0)
	v_mul_f32_e32 v160, v18, v175
	v_fmac_f32_e32 v160, v16, v174
	v_fmac_f32_e32 v161, v21, v162
	v_fmac_f32_e32 v160, v22, v176
	v_fmac_f32_e32 v161, v25, v163
	v_fmac_f32_e32 v160, v23, v177
	v_add_f32_e32 v159, v159, v161
	v_add_f32_e32 v173, v173, v160
	ds_read_b128 v[160:163], v87 offset:1840
	ds_read_b128 v[174:177], v87 offset:1904
	v_mul_f32_e32 v157, 0xbfb8aa3b, v157
	v_exp_f32_e32 v157, v157
	v_add_f32_e32 v153, 1.0, v153
	s_waitcnt lgkmcnt(1)
	v_mul_f32_e32 v161, v9, v161
	v_fmac_f32_e32 v161, v6, v160
	v_fmac_f32_e32 v161, v10, v162
	v_fmac_f32_e32 v161, v11, v163
	v_add_f32_e32 v159, v159, v161
	v_med3_f32 v159, v159, s66, v170
	v_mul_f32_e32 v159, 0xbfb8aa3b, v159
	s_waitcnt lgkmcnt(0)
	v_mul_f32_e32 v160, v5, v175
	v_exp_f32_e32 v159, v159
	v_fmac_f32_e32 v160, v4, v174
	v_fmac_f32_e32 v160, v7, v176
	v_fmac_f32_e32 v160, v8, v177
	v_add_f32_e32 v160, v173, v160
	v_add_f32_e32 v159, 1.0, v159
	v_log_f32_e32 v173, v159
	v_med3_f32 v159, v160, s66, v170
	ds_read_b128 v[160:163], v87 offset:1920
	ds_read_b128 v[174:177], v87 offset:1984
	v_mul_f32_e32 v159, 0xbfb8aa3b, v159
	v_exp_f32_e32 v159, v159
	v_log_f32_e32 v153, v153
	s_waitcnt lgkmcnt(1)
	v_mul_f32_e32 v31, v31, v161
	s_waitcnt lgkmcnt(0)
	v_mul_f32_e32 v30, v30, v175
	v_fmac_f32_e32 v31, v27, v160
	v_fmac_f32_e32 v30, v28, v174
	v_fmac_f32_e32 v31, v32, v162
	v_fmac_f32_e32 v30, v33, v176
	v_fmac_f32_e32 v31, v97, v163
	v_fmac_f32_e32 v30, v96, v177
	v_add_f32_e32 v27, v126, v31
	v_add_f32_e32 v3, v3, v30
	ds_read_b128 v[30:33], v87 offset:1936
	ds_read_b128 v[160:163], v87 offset:2000
	v_add_f32_e32 v159, 1.0, v159
	v_log_f32_e32 v178, v159
	v_fmamk_f32 v159, v128, 0xbd800000, v125
	s_waitcnt lgkmcnt(1)
	v_mul_f32_e32 v15, v15, v31
	v_fmac_f32_e32 v15, v13, v30
	s_waitcnt lgkmcnt(0)
	v_mul_f32_e32 v13, v14, v161
	v_fmac_f32_e32 v13, v12, v160
	v_fmac_f32_e32 v15, v20, v32
	v_fmac_f32_e32 v13, v24, v162
	v_fmac_f32_e32 v15, v29, v33
	v_fmac_f32_e32 v13, v26, v163
	v_add_f32_e32 v20, v27, v15
	v_add_f32_e32 v3, v3, v13
	ds_read_b128 v[12:15], v87 offset:1952
	ds_read_b128 v[26:29], v87 offset:2016
	v_fmamk_f32 v126, v136, 0xbd800000, v159
	v_fmamk_f32 v96, v138, 0xbd800000, v126
	v_fmamk_f32 v32, v140, 0xbd800000, v96
	s_waitcnt lgkmcnt(1)
	v_mul_f32_e32 v13, v19, v13
	v_fmac_f32_e32 v13, v17, v12
	s_waitcnt lgkmcnt(0)
	v_mul_f32_e32 v12, v18, v27
	v_fmac_f32_e32 v12, v16, v26
	v_fmac_f32_e32 v13, v21, v14
	v_fmac_f32_e32 v12, v22, v28
	v_fmac_f32_e32 v13, v25, v15
	v_fmac_f32_e32 v12, v23, v29
	v_add_f32_e32 v20, v20, v13
	v_add_f32_e32 v3, v3, v12
	ds_read_b128 v[12:15], v87 offset:1968
	ds_read_b128 v[16:19], v87 offset:2032
	v_fmamk_f32 v30, v142, 0xbd800000, v32
	v_fmamk_f32 v28, v144, 0xbd800000, v30
	v_add_f32_e32 v155, 1.0, v155
	s_waitcnt lgkmcnt(1)
	v_mul_f32_e32 v9, v9, v13
	s_waitcnt lgkmcnt(0)
	v_mul_f32_e32 v5, v5, v17
	v_fmac_f32_e32 v5, v4, v16
	v_fmac_f32_e32 v5, v7, v18
	v_fmac_f32_e32 v5, v8, v19
	v_add_f32_e32 v3, v3, v5
	v_med3_f32 v3, v3, s66, v170
	v_mul_f32_e32 v3, 0xbfb8aa3b, v3
	v_exp_f32_e32 v3, v3
	v_fmac_f32_e32 v9, v6, v12
	v_fmac_f32_e32 v9, v10, v14
	v_fmac_f32_e32 v9, v11, v15
	v_add_f32_e32 v3, 1.0, v3
	v_log_f32_e32 v3, v3
	v_add_f32_e32 v6, v20, v9
	v_med3_f32 v4, v6, s66, v170
	v_mul_f32_e32 v4, 0xbfb8aa3b, v4
	v_mul_f32_e32 v10, 0xbd800000, v3
	v_fmamk_f32 v13, v178, 0xbd800000, v10
	v_fmamk_f32 v15, v158, 0xbd800000, v13
	v_fmamk_f32 v17, v156, 0xbd800000, v15
	v_fmamk_f32 v19, v154, 0xbd800000, v17
	v_exp_f32_e32 v4, v4
	v_fmamk_f32 v21, v152, 0xbd800000, v19
	v_fmamk_f32 v26, v146, 0xbd800000, v28
	v_fmamk_f32 v23, v150, 0xbd800000, v21
	v_log_f32_e32 v155, v155
	v_add_f32_e32 v157, 1.0, v157
	v_fmamk_f32 v24, v148, 0xbd800000, v26
	v_fmamk_f32 v25, v147, 0xbd800000, v23
	v_log_f32_e32 v157, v157
	v_fmamk_f32 v22, v149, 0xbd800000, v24
	v_fmamk_f32 v27, v145, 0xbd800000, v25
	v_add_f32_e32 v4, 1.0, v4
	v_fmamk_f32 v20, v151, 0xbd800000, v22
	v_fmamk_f32 v29, v143, 0xbd800000, v27
	v_log_f32_e32 v4, v4
	v_fmamk_f32 v18, v153, 0xbd800000, v20
	v_fmamk_f32 v31, v141, 0xbd800000, v29
	v_fmamk_f32 v16, v155, 0xbd800000, v18
	v_fmamk_f32 v33, v139, 0xbd800000, v31
	v_fmamk_f32 v14, v157, 0xbd800000, v16
	v_fmamk_f32 v97, v137, 0xbd800000, v33
	v_fmamk_f32 v12, v173, 0xbd800000, v14
	v_fmamk_f32 v128, v129, 0xbd800000, v97
	v_fmamk_f32 v11, v4, 0xbd800000, v12
	v_fmamk_f32 v127, v127, 0xbd800000, v128
	v_fmamk_f32 v129, v2, 0xbd800000, v127
	ds_write_b32 v98, v11
	ds_write_b32 v100, v129 offset:2048
	s_waitcnt lgkmcnt(0)
	s_barrier
	ds_read2st64_b32 v[4:5], v99 offset1:2
	ds_read2st64_b32 v[2:3], v99 offset0:8 offset1:10
	ds_read2st64_b32 v[8:9], v99 offset0:4 offset1:6
	ds_read2st64_b32 v[6:7], v99 offset0:12 offset1:14
	s_waitcnt lgkmcnt(3)
	v_add_f32_e32 v136, 0, v4
	s_waitcnt lgkmcnt(2)
	v_add_f32_e32 v137, 0, v2
	v_add_f32_e32 v2, v136, v5
	v_add_f32_e32 v4, v137, v3
	s_waitcnt lgkmcnt(1)
	v_add_f32_e32 v2, v2, v8
	s_waitcnt lgkmcnt(0)
	v_add_f32_e32 v4, v4, v6
	v_add_f32_e32 v2, v2, v9
	v_add_f32_e32 v138, v4, v7
	v_exp_f32_e32 v4, v2
	v_exp_f32_e32 v2, v138
	s_and_saveexec_b64 s[78:79], s[36:37]
	s_cbranch_execz .LBB0_425
	s_add_u32 s80, s88, 0x8000
	s_addc_u32 s81, s89, 0
	v_lshlrev_b32_e32 v140, 2, v86
	v_lshl_add_u64 v[138:139], v[70:71], 2, s[80:81]
	global_store_dword v140, v4, s[80:81]
	global_store_dword v[138:139], v2, off offset:512
